# S14 plus one static s_setprio 1 for waves 4-7 during the attention phases (reset at phase exit)
# baseline (speedup 1.0000x reference)
; __device__ __forceinline__ void unit(LAS unsigned char* lds, int b, int h, int qb, const bf16_t* Q, const bf16_t* Kn, const bf16_t* Kr, const bf16_t* VT, const bf16_t* proj, bf16_t* ymix, int wv) {
;     ...
;     const bool shift = wave >= 4;
; __device__ __forceinline__ void phase(LAS unsigned char* lds, const bf16_t* Q, const bf16_t* Kn, const bf16_t* Kr, const bf16_t* VT, const bf16_t* proj, bf16_t* ymix, int vcu, int G, int wv) {
;     for (int n = vcu; n < 1024; n += G) {
;         const int i = n >> 8, c = n & 255, bh = c >> 1, par = c & 1;
;         const int qb = par ? (5 - i) : (i < 2 ? 7 - i : 3 - i);
;         unit(lds, bh >> 3, bh & 7, qb, Q, Kn, Kr, VT, proj, ymix, wv);
.LBB0_602:
	s_or_b64 exec, exec, s[12:13]
	s_cmpk_lt_i32 s3, 0x400
	s_cselect_b64 s[8:9], -1, 0
	v_writelane_b32 v254, s8, 32
	s_cmpk_gt_i32 s3, 0x3ff
	s_waitcnt lgkmcnt(0)
	s_barrier
	v_writelane_b32 v254, s9, 33
	s_cbranch_scc1 .LBB0_633
	v_readlane_b32 s99, v254, 20
	s_nop 0
	s_cmp_lt_u32 s99, 0x80
	s_cbranch_scc1 .Lprio_a
	s_setprio 1
.Lprio_a:
	s_mov_b32 s13, 0
	v_mov_b64_e32 v[204:205], s[54:55]
	v_mov_b32_e32 v1, 0
	s_movk_i32 s27, 0x190
	s_mov_b32 s37, 0x400000
	s_mov_b32 s42, 0x12c00
	s_mov_b32 s43, 0x20000
	s_mov_b32 s44, 0x30000
	s_movk_i32 s45, 0x2000
	s_mov_b32 s64, 0xff800000
	s_mov_b32 s65, 0x41000000
	s_movk_i32 s66, 0x2400
	s_mov_b64 s[16:17], 0x1000
	s_movk_i32 s67, 0x1000
	v_mov_b32_e32 v224, 0xff800000
	s_mov_b32 s68, s3
	s_branch .LBB0_606

; #define LAS __attribute__((address_space(3)))
; __device__ __forceinline__ int lane_id() { return (int)__builtin_amdgcn_mbcnt_hi(~0u, __builtin_amdgcn_mbcnt_lo(~0u, 0u)); }
; __device__ __forceinline__ unsigned xb_add(unsigned* p, unsigned v) { return __hip_atomic_fetch_add(p, v, __ATOMIC_RELAXED, __HIP_MEMORY_SCOPE_AGENT); }
; __device__ __forceinline__ unsigned xb_xcc_id() { return (unsigned)__builtin_amdgcn_s_getreg((3 << 11) | 20) & 0xFu; }
; __device__ __forceinline__ void xcd_barrier(unsigned* bar, LAS unsigned char* lds, int wv) {
;     asm volatile("s_waitcnt vmcnt(0)" ::: "memory");
;     __syncthreads();
;     int lane = lane_id(); asm volatile("" : "+v"(lane));
;     if (wv == 0 && lane == 0) {
;         volatile LAS unsigned* st = (volatile LAS unsigned*)(lds + XB_LDS_OFF);
;         const unsigned x = xb_xcc_id();
;         __builtin_amdgcn_s_waitcnt(0);
;         unsigned nloc = st[0], nx = st[1];
;         if (nloc == 0u) { (void)xb_add(&bar[XB_XCNT(x)], 1u); xcd_barrier_complete(bar, x, nloc, nx); st[0] = nloc; st[1] = nx; }
;         const unsigned old = xb_add(&bar[XB_XSUB(x)], 1u);
.LBB0_633:
	s_setprio 0
	s_waitcnt vmcnt(0)
	v_mov_b32_e32 v0, v222
	v_readlane_b32 s8, v254, 12
	s_barrier
	v_readlane_b32 s9, v254, 13
	v_cmp_eq_u32_e32 vcc, 0, v0
	s_and_b64 s[8:9], s[8:9], vcc
	s_and_saveexec_b64 s[12:13], s[8:9]
	s_cbranch_execz .LBB0_687
	s_add_i32 s9, 0, 0x20040
	v_mov_b32_e32 v0, s9
	s_load_dwordx2 s[16:17], s[94:95], 0xa0
	s_getreg_b32 s8, hwreg(HW_REG_XCC_ID, 0, 4)
	s_waitcnt vmcnt(0) expcnt(0) lgkmcnt(0)
	ds_read_b32 v2, v0
	s_add_i32 s9, 0, 0x20044
	v_mov_b32_e32 v0, s9
	ds_read_b32 v0, v0
	s_and_b32 s9, s8, 15
	s_waitcnt lgkmcnt(1)
	v_cmp_ne_u32_e32 vcc, 0, v2
	s_lshl_b32 s8, s9, 6
	s_cbranch_vccnz .LBB0_651
	s_mov_b64 s[48:49], exec
	s_waitcnt lgkmcnt(0)
	v_mbcnt_lo_u32_b32 v0, s48, 0
	v_mbcnt_hi_u32_b32 v0, s49, v0
	v_cmp_eq_u32_e32 vcc, 0, v0
	s_and_saveexec_b64 s[22:23], vcc
	s_cbranch_execz .LBB0_637
	s_lshl_b32 s14, s8, 2
	s_bcnt1_i32_b64 s15, s[48:49]
	v_mov_b32_e32 v0, s14
	v_mov_b32_e32 v1, s15
	global_atomic_add v0, v1, s[16:17] offset:1024

; __device__ __forceinline__ void phase(LAS unsigned char* lds, const bf16_t* Q, const bf16_t* Kn, const bf16_t* Kr, const bf16_t* VT, const bf16_t* proj, bf16_t* ymix, int vcu, int G, int wv) {
;     for (int n = vcu; n < 1024; n += G) {
;         const int i = n >> 8, c = n & 255, bh = c >> 1, par = c & 1;
;         const int qb = par ? (5 - i) : (i < 2 ? 7 - i : 3 - i);
;         unit(lds, bh >> 3, bh & 7, qb, Q, Kn, Kr, VT, proj, ymix, wv);
.LBB0_1167:
	s_or_b64 exec, exec, s[6:7]
	v_readlane_b32 s0, v254, 32
	v_readlane_b32 s1, v254, 33
	s_andn2_b64 vcc, exec, s[0:1]
	s_waitcnt lgkmcnt(0)
	s_barrier
	s_cbranch_vccnz .LBB0_1198
	v_readlane_b32 s99, v254, 20
	s_nop 0
	s_cmp_lt_u32 s99, 0x80
	s_cbranch_scc1 .Lprio_b
	s_setprio 1
.Lprio_b:
	s_mov_b32 s7, 0
	s_movk_i32 s0, 0xc00
	v_mov_b64_e32 v[204:205], s[16:17]
	v_mov_b32_e32 v1, 0
	s_movk_i32 s1, 0x88
	s_movk_i32 s27, 0x190
	s_mov_b32 s42, 0x10000
	s_mov_b64 s[8:9], 0x400000
	s_mov_b32 s43, 0x400000
	s_mov_b32 s44, 0x12c00
	s_mov_b32 s45, 0x20000
	s_mov_b32 s50, 0x30000
	s_movk_i32 s51, 0x2000
	s_mov_b32 s52, 0xff800000
	s_mov_b32 s53, 0x41000000
	s_movk_i32 s54, 0x2400
	s_mov_b64 s[10:11], 0x1000
	s_movk_i32 s55, 0x1000
	v_mov_b32_e32 v224, 0xff800000
	s_branch .LBB0_1171

; #define LAS __attribute__((address_space(3)))
; __device__ __forceinline__ int lane_id() { return (int)__builtin_amdgcn_mbcnt_hi(~0u, __builtin_amdgcn_mbcnt_lo(~0u, 0u)); }
; __device__ __forceinline__ unsigned xb_add(unsigned* p, unsigned v) { return __hip_atomic_fetch_add(p, v, __ATOMIC_RELAXED, __HIP_MEMORY_SCOPE_AGENT); }
; __device__ __forceinline__ unsigned xb_xcc_id() { return (unsigned)__builtin_amdgcn_s_getreg((3 << 11) | 20) & 0xFu; }
; __device__ __forceinline__ void xcd_barrier(unsigned* bar, LAS unsigned char* lds, int wv) {
;     asm volatile("s_waitcnt vmcnt(0)" ::: "memory");
;     __syncthreads();
;     int lane = lane_id(); asm volatile("" : "+v"(lane));
;     if (wv == 0 && lane == 0) {
;         volatile LAS unsigned* st = (volatile LAS unsigned*)(lds + XB_LDS_OFF);
;         const unsigned x = xb_xcc_id();
;         __builtin_amdgcn_s_waitcnt(0);
;         unsigned nloc = st[0], nx = st[1];
;         if (nloc == 0u) { (void)xb_add(&bar[XB_XCNT(x)], 1u); xcd_barrier_complete(bar, x, nloc, nx); st[0] = nloc; st[1] = nx; }
;         const unsigned old = xb_add(&bar[XB_XSUB(x)], 1u);
.LBB0_1198:
	s_setprio 0
	s_waitcnt vmcnt(0)
	v_mov_b32_e32 v0, v222
	v_readlane_b32 s0, v254, 12
	s_barrier
	v_readlane_b32 s1, v254, 13
	v_cmp_eq_u32_e32 vcc, 0, v0
	s_and_b64 s[0:1], s[0:1], vcc
	s_and_saveexec_b64 s[6:7], s[0:1]
	s_cbranch_execz .LBB0_1252
	s_add_i32 s1, 0, 0x20040
	v_mov_b32_e32 v0, s1
	s_load_dwordx2 s[8:9], s[94:95], 0xa0
	s_getreg_b32 s0, hwreg(HW_REG_XCC_ID, 0, 4)
	s_waitcnt vmcnt(0) expcnt(0) lgkmcnt(0)
	ds_read_b32 v2, v0
	s_add_i32 s1, 0, 0x20044
	v_mov_b32_e32 v0, s1
	ds_read_b32 v0, v0
	s_and_b32 s1, s0, 15
	s_waitcnt lgkmcnt(1)
	v_cmp_ne_u32_e32 vcc, 0, v2
	s_lshl_b32 s0, s1, 6
	s_cbranch_vccnz .LBB0_1216
	s_mov_b64 s[14:15], exec
	s_waitcnt lgkmcnt(0)
	v_mbcnt_lo_u32_b32 v0, s14, 0
	v_mbcnt_hi_u32_b32 v0, s15, v0
	v_cmp_eq_u32_e32 vcc, 0, v0
	s_and_saveexec_b64 s[10:11], vcc
	s_cbranch_execz .LBB0_1202
	s_lshl_b32 s3, s0, 2
	s_bcnt1_i32_b64 s14, s[14:15]
	v_mov_b32_e32 v0, s3
	v_mov_b32_e32 v1, s14
	global_atomic_add v0, v1, s[8:9] offset:1024
